# v44 + XCD-affine attention work queues: one queue per XCD so each XCD only processes its own batch (K/V tiles stay in that XCD's L2)
# speedup vs baseline: 1.0098x; 1.0016x over previous
.LBB0_500:
	s_or_b64 exec, exec, s[0:1]
	v_readlane_b32 s86, v249, 39
	s_cmpk_gt_i32 s64, 0x3ff
	v_readlane_b32 s87, v249, 40
	s_waitcnt lgkmcnt(0)
	s_barrier
	s_cbranch_scc1 .LBB0_747
	s_add_u32 s0, s78, 0x103700
	s_addc_u32 s1, s79, 0
	v_writelane_b32 v248, s64, 5
	s_and_b32 s2, s64, 7
	s_lshl_b32 s2, s2, 5
	s_cmp_eq_u32 s88, 0x100
	s_cselect_b32 s2, s2, 0
	s_add_u32 s0, s0, s2
	s_addc_u32 s1, s1, 0
	v_writelane_b32 v249, s0, 57
	v_mbcnt_hi_u32_b32 v155, -1, v194
	v_and_b32_e32 v0, 64, v155
	v_writelane_b32 v249, s1, 58
	s_add_i32 s0, 0, 0x19e00
	v_writelane_b32 v249, s0, 53
	s_add_i32 s0, 0, 0x1de00
	v_mov_b32_e32 v1, 0
	s_movk_i32 s85, 0x600
	s_movk_i32 s34, 0x48
	s_movk_i32 s35, 0x104
	v_mov_b32_e32 v154, 0x358637bd
	s_mov_b32 s33, 0xefa18f08
	v_xor_b32_e32 v156, 32, v155
	v_add_u32_e32 v157, 64, v0
	v_mov_b32_e32 v158, 0xf149f2ca
	v_mov_b32_e32 v159, 0x7149f2ca
	v_mov_b32_e32 v160, 0x2080
	v_mov_b32_e32 v161, 0x461c4000
	v_mov_b32_e32 v162, 0xffffff80
	v_mov_b32_e32 v163, 0x63
	v_writelane_b32 v249, s0, 55
	s_add_i32 s0, 0, 0x20180
	s_lshr_b32 s6, s64, 3
	s_cmp_eq_u32 s88, 0x100
	s_cselect_b32 s6, s6, s64
	s_mov_b32 s83, 0
	s_mov_b32 s84, 0x41800000
	v_writelane_b32 v249, s0, 51
	s_branch .LBB0_503
.LBB0_502:
	s_or_b64 exec, exec, s[0:1]
	v_readlane_b32 s0, v249, 51
	s_waitcnt lgkmcnt(0)
	s_barrier
	v_mov_b32_e32 v0, s0
	ds_read_b32 v0, v0
	s_movk_i32 s0, 0x400
	s_cmp_eq_u32 s88, 0x100
	s_cselect_b32 s0, 0xa0, s0
	s_waitcnt lgkmcnt(0)
	s_barrier
	v_cmp_gt_i32_e32 vcc, s0, v0
	v_readfirstlane_b32 s6, v0
	s_cbranch_vccz .LBB0_746

.LBB0_506:
	s_or_b64 exec, exec, s[2:3]
	s_waitcnt vmcnt(0)
	v_readfirstlane_b32 s2, v2
	s_cmp_eq_u32 s88, 0x100
	s_cselect_b32 s3, 32, s88
	s_add_i32 s2, s3, s2
	s_nop 0
	v_add_u32_e32 v164, s2, v0
.LBB0_507:
	s_or_b64 exec, exec, s[0:1]
	s_cmp_lg_u32 s88, 0x100
	s_cbranch_scc1 .Lp3_attn
	v_readlane_b32 s2, v248, 5
	s_mul_hi_u32 s0, s6, 0xcccccccd
	s_lshr_b32 s0, s0, 2
	s_mul_i32 s1, s0, 5
	s_sub_i32 s1, s6, s1
	s_and_b32 s2, s2, 7
	s_cmp_eq_u32 s1, 4
	s_cbranch_scc0 .Lp3_dec_attn
	s_lshl_b32 s2, s2, 5
	s_add_i32 s0, s0, s2
	s_branch .Lp3_conv
.Lp3_dec_attn:
	s_lshl_b32 s0, s0, 2
	s_add_i32 s6, s0, s1
	s_lshl_b32 s6, s6, 3
	s_or_b32 s6, s6, s2
